# stack + convert_x unrolled: four items per thread per iteration (eight 16-byte loads in flight), original loop kept as tail
# baseline (speedup 1.0000x reference)
; __device__ __forceinline__ int opaque_tid() { int t = threadIdx.x; asm volatile("" : "+v"(t)); return t; }
; __device__ __forceinline__ u32x4 pack8(const f32x4 a, const f32x4 b) { u32x4 w; w.x = cvt_pk_bf16(a[0], a[1]); w.y = cvt_pk_bf16(a[2], a[3]); w.z = cvt_pk_bf16(b[0], b[1]); w.w = cvt_pk_bf16(b[2], b[3]); return w; }
; __device__ __forceinline__ void convert_x(const float* xp, const float* xs, size_t grow0, bf16_t* XB) {
;     const size_t n8 = (size_t)TC * DM / 8;
;     for (size_t i = (size_t)blockIdx.x * 512 + opaque_tid(); i < n8; i += (size_t)gridDim.x * 512) {
;         const float* x = xrow_ptr(xp, xs, grow0 + (i >> 7)) + (i & 127) * 8;
;         const f32x4 a = *(const f32x4*)x, b = *(const f32x4*)(x + 4);
;         *(u32x4*)(XB + i * 8) = pack8(a, b);
;     }
.LBB0_118:
	v_mov_b32_e32 v4, v250
	v_readlane_b32 s4, v251, 22
	v_readlane_b32 s5, v251, 23
	v_ashrrev_i32_e32 v5, 31, v4
	s_mov_b64 s[14:15], 0x600000
	v_lshl_add_u64 v[0:1], s[4:5], 0, v[4:5]
	v_cmp_gt_u64_e32 vcc, s[14:15], v[0:1]
	s_and_saveexec_b64 s[14:15], vcc
	v_readlane_b32 s20, v254, 9
	v_readlane_b32 s26, v254, 11
	v_readlane_b32 s21, v254, 10
	v_readlane_b32 s27, v254, 12
	s_cbranch_execz .LBB0_121
	v_readlane_b32 s4, v254, 7
	v_readlane_b32 s5, v254, 8
	s_mov_b64 s[16:17], 0
	s_nop 0
	v_lshl_add_u64 v[2:3], v[4:5], 4, s[4:5]
	v_readlane_b32 s4, v254, 37
	v_readlane_b32 s5, v254, 38
	s_nop 1
	v_lshl_add_u64 v[4:5], v[4:5], 3, s[4:5]
	s_lshl_b64 s[98:99], s[12:13], 2
	s_lshl_b64 s[100:101], s[20:21], 2
.Lcvt_main:
	v_lshl_add_u64 v[14:15], v[0:1], 0, s[12:13]
	v_lshl_add_u64 v[16:17], v[14:15], 0, s[12:13]
	v_lshl_add_u64 v[18:19], v[16:17], 0, s[12:13]
	s_mov_b64 s[18:19], 0x600000
	v_cmp_gt_u64_e32 vcc, s[18:19], v[18:19]
	s_nop 1
	s_and_b64 s[18:19], vcc, exec
	s_cmp_eq_u64 s[18:19], exec
	s_cbranch_scc0 .Lcvt_tail
	s_brev_b32 s18, 15
	s_mov_b32 s19, -1
	v_and_b32_e32 v56, 0x3f8, v4
	v_lshlrev_b32_e32 v56, 2, v56
	v_mov_b32_e32 v57, 0
	v_alignbit_b32 v52, v1, v0, 7
	v_add_u32_e32 v52, s30, v52
	v_mov_b32_e32 v53, 0
	v_cmp_gt_u32_e32 vcc, 0x10000, v52
	v_lshlrev_b64 v[54:55], 12, v[52:53]
	v_lshl_add_u64 v[52:53], s[76:77], 0, v[54:55]
	v_lshl_add_u64 v[54:55], s[78:79], 0, v[54:55]
	v_lshl_add_u64 v[54:55], v[54:55], 0, s[18:19]
	v_cndmask_b32_e32 v55, v55, v53, vcc
	v_cndmask_b32_e32 v54, v54, v52, vcc
	v_lshl_add_u64 v[54:55], v[54:55], 0, v[56:57]
	global_load_dwordx4 v[20:23], v[54:55], off
	global_load_dwordx4 v[24:27], v[54:55], off offset:16
	v_alignbit_b32 v52, v15, v14, 7
	v_add_u32_e32 v52, s30, v52
	v_mov_b32_e32 v53, 0
	v_cmp_gt_u32_e32 vcc, 0x10000, v52
	v_lshlrev_b64 v[54:55], 12, v[52:53]
	v_lshl_add_u64 v[52:53], s[76:77], 0, v[54:55]
	v_lshl_add_u64 v[54:55], s[78:79], 0, v[54:55]
	v_lshl_add_u64 v[54:55], v[54:55], 0, s[18:19]
	v_cndmask_b32_e32 v55, v55, v53, vcc
	v_cndmask_b32_e32 v54, v54, v52, vcc
	v_lshl_add_u64 v[54:55], v[54:55], 0, v[56:57]
	global_load_dwordx4 v[28:31], v[54:55], off
	global_load_dwordx4 v[32:35], v[54:55], off offset:16
	v_alignbit_b32 v52, v17, v16, 7
	v_add_u32_e32 v52, s30, v52
	v_mov_b32_e32 v53, 0
	v_cmp_gt_u32_e32 vcc, 0x10000, v52
	v_lshlrev_b64 v[54:55], 12, v[52:53]
	v_lshl_add_u64 v[52:53], s[76:77], 0, v[54:55]
	v_lshl_add_u64 v[54:55], s[78:79], 0, v[54:55]
	v_lshl_add_u64 v[54:55], v[54:55], 0, s[18:19]
	v_cndmask_b32_e32 v55, v55, v53, vcc
	v_cndmask_b32_e32 v54, v54, v52, vcc
	v_lshl_add_u64 v[54:55], v[54:55], 0, v[56:57]
	global_load_dwordx4 v[36:39], v[54:55], off
	global_load_dwordx4 v[40:43], v[54:55], off offset:16
	v_alignbit_b32 v52, v19, v18, 7
	v_add_u32_e32 v52, s30, v52
	v_mov_b32_e32 v53, 0
	v_cmp_gt_u32_e32 vcc, 0x10000, v52
	v_lshlrev_b64 v[54:55], 12, v[52:53]
	v_lshl_add_u64 v[52:53], s[76:77], 0, v[54:55]
	v_lshl_add_u64 v[54:55], s[78:79], 0, v[54:55]
	v_lshl_add_u64 v[54:55], v[54:55], 0, s[18:19]
	v_cndmask_b32_e32 v55, v55, v53, vcc
	v_cndmask_b32_e32 v54, v54, v52, vcc
	v_lshl_add_u64 v[54:55], v[54:55], 0, v[56:57]
	global_load_dwordx4 v[44:47], v[54:55], off
	global_load_dwordx4 v[48:51], v[54:55], off offset:16
	v_lshl_add_u64 v[58:59], v[2:3], 0, s[20:21]
	v_lshl_add_u64 v[60:61], v[58:59], 0, s[20:21]
	v_lshl_add_u64 v[62:63], v[60:61], 0, s[20:21]
	s_waitcnt vmcnt(6)
	v_cvt_pk_bf16_f32 v64, v20, v21
	v_cvt_pk_bf16_f32 v65, v22, v23
	v_cvt_pk_bf16_f32 v66, v24, v25
	v_cvt_pk_bf16_f32 v67, v26, v27
	global_store_dwordx4 v[2:3], v[64:67], off
	s_waitcnt vmcnt(5)
	v_cvt_pk_bf16_f32 v68, v28, v29
	v_cvt_pk_bf16_f32 v69, v30, v31
	v_cvt_pk_bf16_f32 v70, v32, v33
	v_cvt_pk_bf16_f32 v71, v34, v35
	global_store_dwordx4 v[58:59], v[68:71], off
	s_waitcnt vmcnt(4)
	v_cvt_pk_bf16_f32 v72, v36, v37
	v_cvt_pk_bf16_f32 v73, v38, v39
	v_cvt_pk_bf16_f32 v74, v40, v41
	v_cvt_pk_bf16_f32 v75, v42, v43
	global_store_dwordx4 v[60:61], v[72:75], off
	s_waitcnt vmcnt(3)
	v_cvt_pk_bf16_f32 v76, v44, v45
	v_cvt_pk_bf16_f32 v77, v46, v47
	v_cvt_pk_bf16_f32 v78, v48, v49
	v_cvt_pk_bf16_f32 v79, v50, v51
	global_store_dwordx4 v[62:63], v[76:79], off
	v_lshl_add_u64 v[0:1], v[0:1], 0, s[98:99]
	v_lshl_add_u64 v[2:3], v[2:3], 0, s[100:101]
	v_lshl_add_u64 v[4:5], v[4:5], 0, s[26:27]
	v_lshl_add_u64 v[4:5], v[4:5], 0, s[26:27]
	v_lshl_add_u64 v[4:5], v[4:5], 0, s[26:27]
	v_lshl_add_u64 v[4:5], v[4:5], 0, s[26:27]
	s_branch .Lcvt_main
.Lcvt_tail:
	s_mov_b64 s[18:19], 0x600000
	v_cmp_gt_u64_e32 vcc, s[18:19], v[0:1]
	s_nop 1
	s_and_b64 exec, exec, vcc
	s_cbranch_execz .LBB0_121

; __global__ void __launch_bounds__(512) fwd_megakernel(Params p) {
	.amdhsa_kernel _Z14fwd_megakernel6Params
		.amdhsa_group_segment_fixed_size 0
		.amdhsa_private_segment_fixed_size 0
		.amdhsa_kernarg_size 384
		.amdhsa_user_sgpr_count 2
		.amdhsa_user_sgpr_dispatch_ptr 0
		.amdhsa_user_sgpr_queue_ptr 0
		.amdhsa_user_sgpr_kernarg_segment_ptr 1
		.amdhsa_user_sgpr_dispatch_id 0
		.amdhsa_user_sgpr_kernarg_preload_length 0
		.amdhsa_user_sgpr_kernarg_preload_offset 0
		.amdhsa_user_sgpr_private_segment_size 0
		.amdhsa_uses_dynamic_stack 0
		.amdhsa_enable_private_segment 0
		.amdhsa_system_sgpr_workgroup_id_x 1
		.amdhsa_system_sgpr_workgroup_id_y 0
		.amdhsa_system_sgpr_workgroup_id_z 0
		.amdhsa_system_sgpr_workgroup_info 0
		.amdhsa_system_vgpr_workitem_id 2
		.amdhsa_next_free_vgpr 256
		.amdhsa_next_free_sgpr 102
		.amdhsa_accum_offset 256
		.amdhsa_reserve_vcc 1
		.amdhsa_float_round_mode_32 0
		.amdhsa_float_round_mode_16_64 0
		.amdhsa_float_denorm_mode_32 3
		.amdhsa_float_denorm_mode_16_64 3
		.amdhsa_dx10_clamp 1
		.amdhsa_ieee_mode 1
		.amdhsa_fp16_overflow 0
		.amdhsa_tg_split 0
		.amdhsa_exception_fp_ieee_invalid_op 0
		.amdhsa_exception_fp_denorm_src 0
		.amdhsa_exception_fp_ieee_div_zero 0
		.amdhsa_exception_fp_ieee_overflow 0
		.amdhsa_exception_fp_ieee_underflow 0
		.amdhsa_exception_fp_ieee_inexact 0
		.amdhsa_exception_int_div_zero 0
	.end_amdhsa_kernel

; __global__ void __launch_bounds__(512) fwd_megakernel(Params p) {
amdhsa.kernels:
  - .agpr_count:     0
    .args:
      - .offset:         0
        .size:           128
        .value_kind:     by_value
      - .offset:         128
        .size:           4
        .value_kind:     hidden_block_count_x
      - .offset:         132
        .size:           4
        .value_kind:     hidden_block_count_y
      - .offset:         136
        .size:           4
        .value_kind:     hidden_block_count_z
      - .offset:         140
        .size:           2
        .value_kind:     hidden_group_size_x
      - .offset:         142
        .size:           2
        .value_kind:     hidden_group_size_y
      - .offset:         144
        .size:           2
        .value_kind:     hidden_group_size_z
      - .offset:         146
        .size:           2
        .value_kind:     hidden_remainder_x
      - .offset:         148
        .size:           2
        .value_kind:     hidden_remainder_y
      - .offset:         150
        .size:           2
        .value_kind:     hidden_remainder_z
      - .offset:         168
        .size:           8
        .value_kind:     hidden_global_offset_x
      - .offset:         176
        .size:           8
        .value_kind:     hidden_global_offset_y
      - .offset:         184
        .size:           8
        .value_kind:     hidden_global_offset_z
      - .offset:         192
        .size:           2
        .value_kind:     hidden_grid_dims
      - .offset:         216
        .size:           8
        .value_kind:     hidden_multigrid_sync_arg
      - .offset:         248
        .size:           4
        .value_kind:     hidden_dynamic_lds_size
    .group_segment_fixed_size: 0
    .kernarg_segment_align: 8
    .kernarg_segment_size: 384
    .language:       OpenCL C
    .language_version:
      - 2
      - 0
    .max_flat_workgroup_size: 512
    .name:           _Z14fwd_megakernel6Params
    .private_segment_fixed_size: 0
    .sgpr_count:     108
    .sgpr_spill_count: 274
    .symbol:         _Z14fwd_megakernel6Params.kd
    .uniform_work_group_size: 1
    .uses_dynamic_stack: false
    .vgpr_count:     256
    .vgpr_spill_count: 0
    .wavefront_size: 64
